# P6 epilogue: gain vector loaded once per unit (was 32 dependent reloads); P4 epilogue: x loads of a row group issued together with counted waits
# speedup vs baseline: 1.0287x; 1.0079x over previous
; __device__ __forceinline__ unsigned pk2(float lo, float hi) { f32x2_t v = {lo, hi}; bf16x2_t b = __builtin_convertvector(v, bf16x2_t); return __builtin_bit_cast(unsigned, b); }
;     __device__ __forceinline__ void operator()(const f32x4 (&acc)[2][2][4][2], const Unit& u, int wr, int wc, int fr, int fq) const {
;     ...
;             for (int m = 0; m < 4; ++m) { const int row = row0 + ai * HALF + m * 16;
;                 const float* xr = (row < TP ? xp + (size_t)row * DM : xs + (size_t)(row - TP) * DM) + col0;
;                 bf16_t* brow = x1b + (size_t)row * DM + col0; float ss = 0.f;
; #pragma unroll
;                 for (int bj = 0; bj < 2; ++bj)
; #pragma unroll
;                     for (int n = 0; n < 2; ++n) { const int co = bj * HALF + n * 16; const f32x4 v = *(const f32x4*)(xr + co) + acc[ai][bj][m][n] * sc;
;                         u32x2 w; w.x = pk2(v[0], v[1]); w.y = pk2(v[2], v[3]); *(u32x2*)(brow + co) = w;
;                         ss += (v[0] * v[0] + v[1] * v[1]) + (v[2] * v[2] + v[3] * v[3]); }
;                 ss += __shfl_xor(ss, 16); ss += __shfl_xor(ss, 32);
;                 if (fq == 0) ssq[(size_t)row * 16 + u.pn * 4 + wc] = ss; }
.LBB0_786:
	s_or_b64 exec, exec, s[52:53]
	s_lshl_b32 s9, s8, 8
	v_ashrrev_i32_e32 v18, 2, v26
	s_or_b32 s9, s9, s83
	v_and_b32_e32 v18, -4, v18
	v_add_u32_e32 v18, s9, v18
	v_ashrrev_i32_e32 v19, 31, v18
	v_lshl_add_u64 v[24:25], v[18:19], 2, v[24:25]
	global_load_dwordx4 v[40:43], v[24:25], off
	global_load_dwordx4 v[200:203], v[24:25], off offset:64
	global_load_dwordx4 v[204:207], v[24:25], off offset:512
	global_load_dwordx4 v[208:211], v[24:25], off offset:576
	v_lshlrev_b64 v[154:155], 11, v[16:17]
	v_lshl_add_u64 v[154:155], s[2:3], 0, v[154:155]
	v_lshl_add_u64 v[154:155], v[18:19], 1, v[154:155]
	v_xor_b32_e32 v27, 32, v153
	s_lshl_b32 s52, s8, 2
	s_ashr_i32 s53, s52, 31
	s_waitcnt vmcnt(3)
	v_pk_add_f32 v[142:143], v[142:143], v[42:43]
	v_pk_add_f32 v[144:145], v[144:145], v[40:41]
	v_cvt_pk_bf16_f32 v41, v142, v143
	v_cvt_pk_bf16_f32 v40, v144, v145
	global_store_dwordx2 v[154:155], v[40:41], off
	s_waitcnt vmcnt(3)
	v_mov_b64_e32 v[40:41], v[200:201]
	v_mov_b64_e32 v[42:43], v[202:203]
	v_pk_add_f32 v[156:157], v[136:137], v[42:43]
	v_pk_add_f32 v[158:159], v[134:135], v[40:41]
	v_cvt_pk_bf16_f32 v41, v156, v157
	v_cvt_pk_bf16_f32 v40, v158, v159
	global_store_dwordx2 v[154:155], v[40:41], off offset:32
	s_waitcnt vmcnt(3)
	v_mov_b64_e32 v[40:41], v[204:205]
	v_mov_b64_e32 v[42:43], v[206:207]
	v_mul_f32_e32 v128, v157, v157
	v_fmac_f32_e32 v128, v156, v156
	v_pk_add_f32 v[42:43], v[140:141], v[42:43]
	v_pk_add_f32 v[138:139], v[138:139], v[40:41]
	v_cvt_pk_bf16_f32 v41, v42, v43
	v_cvt_pk_bf16_f32 v40, v138, v139
	global_store_dwordx2 v[154:155], v[40:41], off offset:256
	s_waitcnt vmcnt(3)
	v_mov_b64_e32 v[134:135], v[208:209]
	v_mov_b64_e32 v[136:137], v[210:211]
	v_and_b32_e32 v25, 64, v153
	v_xor_b32_e32 v24, 16, v153
	v_add_u32_e32 v25, 64, v25
	v_cmp_lt_i32_e32 vcc, v24, v25
	v_mul_f32_e32 v41, v143, v143
	v_fmac_f32_e32 v41, v142, v142
	v_cndmask_b32_e32 v24, v153, v24, vcc
	v_lshlrev_b32_e32 v40, 2, v24
	v_mul_f32_e32 v24, v145, v145
	v_fmac_f32_e32 v24, v144, v144
	v_add_f32_e32 v24, v24, v41
	v_mul_f32_e32 v41, v159, v159
	v_fmac_f32_e32 v41, v158, v158
	v_add_f32_e32 v41, v41, v128
	v_add_f32_e32 v24, v24, v41
	v_mul_f32_e32 v41, v139, v139
	v_mul_f32_e32 v43, v43, v43
	v_fmac_f32_e32 v41, v138, v138
	v_fmac_f32_e32 v43, v42, v42
	v_add_f32_e32 v41, v41, v43
	v_add_f32_e32 v24, v24, v41
	v_cmp_lt_i32_e32 vcc, v27, v25
	v_pk_add_f32 v[42:43], v[126:127], v[136:137]
	v_pk_add_f32 v[124:125], v[124:125], v[134:135]
	v_mul_f32_e32 v126, v43, v43
	v_mul_f32_e32 v41, v125, v125
	v_fmac_f32_e32 v41, v124, v124
	v_fmac_f32_e32 v126, v42, v42
	v_add_f32_e32 v41, v41, v126
	v_add_f32_e32 v24, v24, v41
	ds_bpermute_b32 v126, v40, v24
	v_cndmask_b32_e32 v25, v153, v27, vcc
	v_lshlrev_b32_e32 v41, 2, v25
	v_cmp_gt_u32_e32 vcc, 16, v26
	v_cvt_pk_bf16_f32 v26, v124, v125
	s_waitcnt lgkmcnt(0)
	v_add_f32_e32 v24, v24, v126
	ds_bpermute_b32 v25, v41, v24
	v_cvt_pk_bf16_f32 v27, v42, v43
	global_store_dwordx2 v[154:155], v[26:27], off offset:288
	s_and_saveexec_b64 s[8:9], vcc
	s_cbranch_execz .LBB0_788
	v_lshlrev_b64 v[26:27], 6, v[16:17]
	v_lshl_add_u64 v[26:27], s[10:11], 0, v[26:27]
	v_lshl_add_u64 v[26:27], s[52:53], 2, v[26:27]
	s_lshl_b32 s40, s82, 2
	v_lshl_add_u64 v[26:27], v[26:27], 0, s[40:41]
	s_waitcnt lgkmcnt(0)
	v_add_f32_e32 v17, v24, v25
	global_store_dword v[26:27], v17, off

; __device__ __forceinline__ unsigned pk2(float lo, float hi) { f32x2_t v = {lo, hi}; bf16x2_t b = __builtin_convertvector(v, bf16x2_t); return __builtin_bit_cast(unsigned, b); }
;     __device__ __forceinline__ void operator()(const f32x4 (&acc)[2][2][4][2], const Unit& u, int wr, int wc, int fr, int fq) const {
;     ...
;             for (int m = 0; m < 4; ++m) { const int row = row0 + ai * HALF + m * 16;
;                 const float* xr = (row < TP ? xp + (size_t)row * DM : xs + (size_t)(row - TP) * DM) + col0;
;                 bf16_t* brow = x1b + (size_t)row * DM + col0; float ss = 0.f;
; #pragma unroll
;                 for (int bj = 0; bj < 2; ++bj)
; #pragma unroll
;                     for (int n = 0; n < 2; ++n) { const int co = bj * HALF + n * 16; const f32x4 v = *(const f32x4*)(xr + co) + acc[ai][bj][m][n] * sc;
;                         u32x2 w; w.x = pk2(v[0], v[1]); w.y = pk2(v[2], v[3]); *(u32x2*)(brow + co) = w;
;                         ss += (v[0] * v[0] + v[1] * v[1]) + (v[2] * v[2] + v[3] * v[3]); }
;                 ss += __shfl_xor(ss, 16); ss += __shfl_xor(ss, 32);
;                 if (fq == 0) ssq[(size_t)row * 16 + u.pn * 4 + wc] = ss; }
.LBB0_792:
	s_or_b64 exec, exec, s[8:9]
	v_lshl_add_u64 v[26:27], v[18:19], 2, v[26:27]
	global_load_dwordx4 v[124:127], v[26:27], off
	global_load_dwordx4 v[200:203], v[26:27], off offset:64
	global_load_dwordx4 v[204:207], v[26:27], off offset:512
	global_load_dwordx4 v[208:211], v[26:27], off offset:576
	v_lshlrev_b64 v[42:43], 11, v[24:25]
	v_lshl_add_u64 v[42:43], s[2:3], 0, v[42:43]
	v_lshl_add_u64 v[42:43], v[18:19], 1, v[42:43]
	s_waitcnt vmcnt(3)
	v_pk_add_f32 v[126:127], v[122:123], v[126:127]
	v_pk_add_f32 v[124:125], v[120:121], v[124:125]
	v_cvt_pk_bf16_f32 v121, v126, v127
	v_cvt_pk_bf16_f32 v120, v124, v125
	global_store_dwordx2 v[42:43], v[120:121], off
	s_waitcnt vmcnt(3)
	v_mov_b64_e32 v[120:121], v[200:201]
	v_mov_b64_e32 v[122:123], v[202:203]
	v_mul_f32_e32 v17, v125, v125
	v_fmac_f32_e32 v17, v124, v124
	v_pk_add_f32 v[122:123], v[114:115], v[122:123]
	v_pk_add_f32 v[120:121], v[112:113], v[120:121]
	v_cvt_pk_bf16_f32 v113, v122, v123
	v_cvt_pk_bf16_f32 v112, v120, v121
	global_store_dwordx2 v[42:43], v[112:113], off offset:32
	s_waitcnt vmcnt(3)
	v_mov_b64_e32 v[112:113], v[204:205]
	v_mov_b64_e32 v[114:115], v[206:207]
	v_pk_add_f32 v[118:119], v[118:119], v[114:115]
	v_pk_add_f32 v[116:117], v[116:117], v[112:113]
	v_cvt_pk_bf16_f32 v113, v118, v119
	v_cvt_pk_bf16_f32 v112, v116, v117
	global_store_dwordx2 v[42:43], v[112:113], off offset:256
	s_waitcnt vmcnt(3)
	v_mov_b64_e32 v[112:113], v[208:209]
	v_mov_b64_e32 v[114:115], v[210:211]
	v_mul_f32_e32 v26, v127, v127
	v_fmac_f32_e32 v26, v126, v126
	v_add_f32_e32 v17, v17, v26
	v_mul_f32_e32 v26, v121, v121
	v_mul_f32_e32 v27, v123, v123
	v_fmac_f32_e32 v26, v120, v120
	v_fmac_f32_e32 v27, v122, v122
	v_add_f32_e32 v26, v26, v27
	v_add_f32_e32 v17, v17, v26
	v_mul_f32_e32 v26, v117, v117
	v_mul_f32_e32 v27, v119, v119
	v_fmac_f32_e32 v26, v116, v116
	v_fmac_f32_e32 v27, v118, v118
	v_add_f32_e32 v26, v26, v27
	v_add_f32_e32 v17, v17, v26
	v_pk_add_f32 v[110:111], v[110:111], v[114:115]
	v_pk_add_f32 v[108:109], v[108:109], v[112:113]
	v_mul_f32_e32 v27, v111, v111
	v_mul_f32_e32 v26, v109, v109
	v_fmac_f32_e32 v26, v108, v108
	v_fmac_f32_e32 v27, v110, v110
	v_add_f32_e32 v26, v26, v27
	v_add_f32_e32 v17, v17, v26
	ds_bpermute_b32 v26, v40, v17
	v_cvt_pk_bf16_f32 v108, v108, v109
	v_cvt_pk_bf16_f32 v109, v110, v111
	global_store_dwordx2 v[42:43], v[108:109], off offset:288
	s_waitcnt lgkmcnt(0)
	v_add_f32_e32 v17, v17, v26
	ds_bpermute_b32 v26, v41, v17
	s_and_saveexec_b64 s[8:9], vcc
	s_cbranch_execz .LBB0_794
	v_lshlrev_b64 v[24:25], 6, v[24:25]
	v_lshl_add_u64 v[24:25], s[10:11], 0, v[24:25]
	v_lshl_add_u64 v[24:25], s[52:53], 2, v[24:25]
	s_lshl_b32 s40, s82, 2
	v_lshl_add_u64 v[24:25], v[24:25], 0, s[40:41]
	s_waitcnt lgkmcnt(0)
	v_add_f32_e32 v17, v17, v26
	global_store_dword v[24:25], v17, off

; __device__ __forceinline__ unsigned pk2(float lo, float hi) { f32x2_t v = {lo, hi}; bf16x2_t b = __builtin_convertvector(v, bf16x2_t); return __builtin_bit_cast(unsigned, b); }
;     __device__ __forceinline__ void operator()(const f32x4 (&acc)[2][2][4][2], const Unit& u, int wr, int wc, int fr, int fq) const {
;     ...
;             for (int m = 0; m < 4; ++m) { const int row = row0 + ai * HALF + m * 16;
;                 const float* xr = (row < TP ? xp + (size_t)row * DM : xs + (size_t)(row - TP) * DM) + col0;
;                 bf16_t* brow = x1b + (size_t)row * DM + col0; float ss = 0.f;
; #pragma unroll
;                 for (int bj = 0; bj < 2; ++bj)
; #pragma unroll
;                     for (int n = 0; n < 2; ++n) { const int co = bj * HALF + n * 16; const f32x4 v = *(const f32x4*)(xr + co) + acc[ai][bj][m][n] * sc;
;                         u32x2 w; w.x = pk2(v[0], v[1]); w.y = pk2(v[2], v[3]); *(u32x2*)(brow + co) = w;
;                         ss += (v[0] * v[0] + v[1] * v[1]) + (v[2] * v[2] + v[3] * v[3]); }
;                 ss += __shfl_xor(ss, 16); ss += __shfl_xor(ss, 32);
;                 if (fq == 0) ssq[(size_t)row * 16 + u.pn * 4 + wc] = ss; }
.LBB0_798:
	s_or_b64 exec, exec, s[8:9]
	s_waitcnt lgkmcnt(0)
	v_lshl_add_u64 v[26:27], v[18:19], 2, v[26:27]
	global_load_dwordx4 v[108:111], v[26:27], off
	global_load_dwordx4 v[200:203], v[26:27], off offset:64
	global_load_dwordx4 v[204:207], v[26:27], off offset:512
	global_load_dwordx4 v[208:211], v[26:27], off offset:576
	v_lshlrev_b64 v[42:43], 11, v[24:25]
	v_lshl_add_u64 v[42:43], s[2:3], 0, v[42:43]
	v_lshl_add_u64 v[42:43], v[18:19], 1, v[42:43]
	s_waitcnt vmcnt(3)
	v_pk_add_f32 v[110:111], v[106:107], v[110:111]
	v_pk_add_f32 v[108:109], v[104:105], v[108:109]
	v_cvt_pk_bf16_f32 v105, v110, v111
	v_cvt_pk_bf16_f32 v104, v108, v109
	global_store_dwordx2 v[42:43], v[104:105], off
	s_waitcnt vmcnt(3)
	v_mov_b64_e32 v[104:105], v[200:201]
	v_mov_b64_e32 v[106:107], v[202:203]
	v_mul_f32_e32 v17, v109, v109
	v_fmac_f32_e32 v17, v108, v108
	v_pk_add_f32 v[106:107], v[98:99], v[106:107]
	v_pk_add_f32 v[104:105], v[96:97], v[104:105]
	v_cvt_pk_bf16_f32 v97, v106, v107
	v_cvt_pk_bf16_f32 v96, v104, v105
	global_store_dwordx2 v[42:43], v[96:97], off offset:32
	s_waitcnt vmcnt(3)
	v_mov_b64_e32 v[96:97], v[204:205]
	v_mov_b64_e32 v[98:99], v[206:207]
	v_pk_add_f32 v[102:103], v[102:103], v[98:99]
	v_pk_add_f32 v[100:101], v[100:101], v[96:97]
	v_cvt_pk_bf16_f32 v97, v102, v103
	v_cvt_pk_bf16_f32 v96, v100, v101
	global_store_dwordx2 v[42:43], v[96:97], off offset:256
	s_waitcnt vmcnt(3)
	v_mov_b64_e32 v[96:97], v[208:209]
	v_mov_b64_e32 v[98:99], v[210:211]
	v_mul_f32_e32 v26, v111, v111
	v_fmac_f32_e32 v26, v110, v110
	v_add_f32_e32 v17, v17, v26
	v_mul_f32_e32 v26, v105, v105
	v_mul_f32_e32 v27, v107, v107
	v_fmac_f32_e32 v26, v104, v104
	v_fmac_f32_e32 v27, v106, v106
	v_add_f32_e32 v26, v26, v27
	v_add_f32_e32 v17, v17, v26
	v_mul_f32_e32 v26, v101, v101
	v_mul_f32_e32 v27, v103, v103
	v_fmac_f32_e32 v26, v100, v100
	v_fmac_f32_e32 v27, v102, v102
	v_add_f32_e32 v26, v26, v27
	v_add_f32_e32 v17, v17, v26
	v_pk_add_f32 v[94:95], v[94:95], v[98:99]
	v_pk_add_f32 v[92:93], v[92:93], v[96:97]
	v_mul_f32_e32 v27, v95, v95
	v_mul_f32_e32 v26, v93, v93
	v_fmac_f32_e32 v26, v92, v92
	v_fmac_f32_e32 v27, v94, v94
	v_add_f32_e32 v26, v26, v27
	v_add_f32_e32 v17, v17, v26
	ds_bpermute_b32 v26, v40, v17
	v_cvt_pk_bf16_f32 v92, v92, v93
	v_cvt_pk_bf16_f32 v93, v94, v95
	global_store_dwordx2 v[42:43], v[92:93], off offset:288
	s_waitcnt lgkmcnt(0)
	v_add_f32_e32 v17, v17, v26
	ds_bpermute_b32 v26, v41, v17
	s_and_saveexec_b64 s[8:9], vcc
	s_cbranch_execz .LBB0_800
	v_lshlrev_b64 v[24:25], 6, v[24:25]
	v_lshl_add_u64 v[24:25], s[10:11], 0, v[24:25]
	v_lshl_add_u64 v[24:25], s[52:53], 2, v[24:25]
	s_lshl_b32 s40, s82, 2
	v_lshl_add_u64 v[24:25], v[24:25], 0, s[40:41]
	s_waitcnt lgkmcnt(0)
	v_add_f32_e32 v17, v17, v26
	global_store_dword v[24:25], v17, off

; __device__ __forceinline__ unsigned pk2(float lo, float hi) { f32x2_t v = {lo, hi}; bf16x2_t b = __builtin_convertvector(v, bf16x2_t); return __builtin_bit_cast(unsigned, b); }
;     __device__ __forceinline__ void operator()(const f32x4 (&acc)[2][2][4][2], const Unit& u, int wr, int wc, int fr, int fq) const {
;     ...
;             for (int m = 0; m < 4; ++m) { const int row = row0 + ai * HALF + m * 16;
;                 const float* xr = (row < TP ? xp + (size_t)row * DM : xs + (size_t)(row - TP) * DM) + col0;
;                 bf16_t* brow = x1b + (size_t)row * DM + col0; float ss = 0.f;
; #pragma unroll
;                 for (int bj = 0; bj < 2; ++bj)
; #pragma unroll
;                     for (int n = 0; n < 2; ++n) { const int co = bj * HALF + n * 16; const f32x4 v = *(const f32x4*)(xr + co) + acc[ai][bj][m][n] * sc;
;                         u32x2 w; w.x = pk2(v[0], v[1]); w.y = pk2(v[2], v[3]); *(u32x2*)(brow + co) = w;
;                         ss += (v[0] * v[0] + v[1] * v[1]) + (v[2] * v[2] + v[3] * v[3]); }
;                 ss += __shfl_xor(ss, 16); ss += __shfl_xor(ss, 32);
;                 if (fq == 0) ssq[(size_t)row * 16 + u.pn * 4 + wc] = ss; }
.LBB0_804:
	s_or_b64 exec, exec, s[8:9]
	s_waitcnt lgkmcnt(0)
	v_lshl_add_u64 v[26:27], v[18:19], 2, v[26:27]
	global_load_dwordx4 v[92:95], v[26:27], off
	global_load_dwordx4 v[200:203], v[26:27], off offset:64
	global_load_dwordx4 v[204:207], v[26:27], off offset:512
	global_load_dwordx4 v[208:211], v[26:27], off offset:576
	v_lshlrev_b64 v[42:43], 11, v[24:25]
	v_lshl_add_u64 v[42:43], s[2:3], 0, v[42:43]
	v_lshl_add_u64 v[42:43], v[18:19], 1, v[42:43]
	s_waitcnt vmcnt(3)
	v_pk_add_f32 v[94:95], v[90:91], v[94:95]
	v_pk_add_f32 v[92:93], v[88:89], v[92:93]
	v_cvt_pk_bf16_f32 v89, v94, v95
	v_cvt_pk_bf16_f32 v88, v92, v93
	global_store_dwordx2 v[42:43], v[88:89], off
	s_waitcnt vmcnt(3)
	v_mov_b64_e32 v[88:89], v[200:201]
	v_mov_b64_e32 v[90:91], v[202:203]
	v_mul_f32_e32 v17, v93, v93
	v_fmac_f32_e32 v17, v92, v92
	v_pk_add_f32 v[90:91], v[82:83], v[90:91]
	v_pk_add_f32 v[88:89], v[80:81], v[88:89]
	v_cvt_pk_bf16_f32 v81, v90, v91
	v_cvt_pk_bf16_f32 v80, v88, v89
	global_store_dwordx2 v[42:43], v[80:81], off offset:32
	s_waitcnt vmcnt(3)
	v_mov_b64_e32 v[80:81], v[204:205]
	v_mov_b64_e32 v[82:83], v[206:207]
	v_pk_add_f32 v[86:87], v[86:87], v[82:83]
	v_pk_add_f32 v[84:85], v[84:85], v[80:81]
	v_cvt_pk_bf16_f32 v81, v86, v87
	v_cvt_pk_bf16_f32 v80, v84, v85
	global_store_dwordx2 v[42:43], v[80:81], off offset:256
	s_waitcnt vmcnt(3)
	v_mov_b64_e32 v[80:81], v[208:209]
	v_mov_b64_e32 v[82:83], v[210:211]
	v_mul_f32_e32 v26, v95, v95
	v_fmac_f32_e32 v26, v94, v94
	v_add_f32_e32 v17, v17, v26
	v_mul_f32_e32 v26, v89, v89
	v_mul_f32_e32 v27, v91, v91
	v_fmac_f32_e32 v26, v88, v88
	v_fmac_f32_e32 v27, v90, v90
	v_add_f32_e32 v26, v26, v27
	v_add_f32_e32 v17, v17, v26
	v_mul_f32_e32 v26, v85, v85
	v_mul_f32_e32 v27, v87, v87
	v_fmac_f32_e32 v26, v84, v84
	v_fmac_f32_e32 v27, v86, v86
	v_add_f32_e32 v26, v26, v27
	v_add_f32_e32 v17, v17, v26
	v_pk_add_f32 v[78:79], v[78:79], v[82:83]
	v_pk_add_f32 v[76:77], v[76:77], v[80:81]
	v_mul_f32_e32 v27, v79, v79
	v_mul_f32_e32 v26, v77, v77
	v_fmac_f32_e32 v26, v76, v76
	v_fmac_f32_e32 v27, v78, v78
	v_add_f32_e32 v26, v26, v27
	v_add_f32_e32 v17, v17, v26
	ds_bpermute_b32 v26, v40, v17
	v_cvt_pk_bf16_f32 v76, v76, v77
	v_cvt_pk_bf16_f32 v77, v78, v79
	global_store_dwordx2 v[42:43], v[76:77], off offset:288
	s_waitcnt lgkmcnt(0)
	v_add_f32_e32 v17, v17, v26
	ds_bpermute_b32 v26, v41, v17
	s_and_saveexec_b64 s[8:9], vcc
	s_cbranch_execz .LBB0_806
	v_lshlrev_b64 v[24:25], 6, v[24:25]
	v_lshl_add_u64 v[24:25], s[10:11], 0, v[24:25]
	v_lshl_add_u64 v[24:25], s[52:53], 2, v[24:25]
	s_lshl_b32 s40, s82, 2
	v_lshl_add_u64 v[24:25], v[24:25], 0, s[40:41]
	s_waitcnt lgkmcnt(0)
	v_add_f32_e32 v17, v17, v26
	global_store_dword v[24:25], v17, off

; __device__ __forceinline__ unsigned pk2(float lo, float hi) { f32x2_t v = {lo, hi}; bf16x2_t b = __builtin_convertvector(v, bf16x2_t); return __builtin_bit_cast(unsigned, b); }
;     __device__ __forceinline__ void operator()(const f32x4 (&acc)[2][2][4][2], const Unit& u, int wr, int wc, int fr, int fq) const {
;     ...
;             for (int m = 0; m < 4; ++m) { const int row = row0 + ai * HALF + m * 16;
;                 const float* xr = (row < TP ? xp + (size_t)row * DM : xs + (size_t)(row - TP) * DM) + col0;
;                 bf16_t* brow = x1b + (size_t)row * DM + col0; float ss = 0.f;
; #pragma unroll
;                 for (int bj = 0; bj < 2; ++bj)
; #pragma unroll
;                     for (int n = 0; n < 2; ++n) { const int co = bj * HALF + n * 16; const f32x4 v = *(const f32x4*)(xr + co) + acc[ai][bj][m][n] * sc;
;                         u32x2 w; w.x = pk2(v[0], v[1]); w.y = pk2(v[2], v[3]); *(u32x2*)(brow + co) = w;
;                         ss += (v[0] * v[0] + v[1] * v[1]) + (v[2] * v[2] + v[3] * v[3]); }
;                 ss += __shfl_xor(ss, 16); ss += __shfl_xor(ss, 32);
;                 if (fq == 0) ssq[(size_t)row * 16 + u.pn * 4 + wc] = ss; }
.LBB0_810:
	s_or_b64 exec, exec, s[8:9]
	s_waitcnt lgkmcnt(0)
	v_lshl_add_u64 v[26:27], v[18:19], 2, v[26:27]
	global_load_dwordx4 v[76:79], v[26:27], off
	global_load_dwordx4 v[200:203], v[26:27], off offset:64
	global_load_dwordx4 v[204:207], v[26:27], off offset:512
	global_load_dwordx4 v[208:211], v[26:27], off offset:576
	v_lshlrev_b64 v[42:43], 11, v[24:25]
	v_lshl_add_u64 v[42:43], s[2:3], 0, v[42:43]
	v_lshl_add_u64 v[42:43], v[18:19], 1, v[42:43]
	s_waitcnt vmcnt(3)
	v_pk_add_f32 v[78:79], v[74:75], v[78:79]
	v_pk_add_f32 v[76:77], v[72:73], v[76:77]
	v_cvt_pk_bf16_f32 v73, v78, v79
	v_cvt_pk_bf16_f32 v72, v76, v77
	global_store_dwordx2 v[42:43], v[72:73], off
	s_waitcnt vmcnt(3)
	v_mov_b64_e32 v[72:73], v[200:201]
	v_mov_b64_e32 v[74:75], v[202:203]
	v_mul_f32_e32 v17, v77, v77
	v_fmac_f32_e32 v17, v76, v76
	v_pk_add_f32 v[74:75], v[66:67], v[74:75]
	v_pk_add_f32 v[72:73], v[64:65], v[72:73]
	v_cvt_pk_bf16_f32 v65, v74, v75
	v_cvt_pk_bf16_f32 v64, v72, v73
	global_store_dwordx2 v[42:43], v[64:65], off offset:32
	s_waitcnt vmcnt(3)
	v_mov_b64_e32 v[64:65], v[204:205]
	v_mov_b64_e32 v[66:67], v[206:207]
	v_pk_add_f32 v[70:71], v[70:71], v[66:67]
	v_pk_add_f32 v[68:69], v[68:69], v[64:65]
	v_cvt_pk_bf16_f32 v65, v70, v71
	v_cvt_pk_bf16_f32 v64, v68, v69
	global_store_dwordx2 v[42:43], v[64:65], off offset:256
	s_waitcnt vmcnt(3)
	v_mov_b64_e32 v[64:65], v[208:209]
	v_mov_b64_e32 v[66:67], v[210:211]
	v_mul_f32_e32 v26, v79, v79
	v_fmac_f32_e32 v26, v78, v78
	v_add_f32_e32 v17, v17, v26
	v_mul_f32_e32 v26, v73, v73
	v_mul_f32_e32 v27, v75, v75
	v_fmac_f32_e32 v26, v72, v72
	v_fmac_f32_e32 v27, v74, v74
	v_add_f32_e32 v26, v26, v27
	v_add_f32_e32 v17, v17, v26
	v_mul_f32_e32 v26, v69, v69
	v_mul_f32_e32 v27, v71, v71
	v_fmac_f32_e32 v26, v68, v68
	v_fmac_f32_e32 v27, v70, v70
	v_add_f32_e32 v26, v26, v27
	v_add_f32_e32 v17, v17, v26
	v_pk_add_f32 v[62:63], v[62:63], v[66:67]
	v_pk_add_f32 v[60:61], v[60:61], v[64:65]
	v_mul_f32_e32 v27, v63, v63
	v_mul_f32_e32 v26, v61, v61
	v_fmac_f32_e32 v26, v60, v60
	v_fmac_f32_e32 v27, v62, v62
	v_add_f32_e32 v26, v26, v27
	v_add_f32_e32 v17, v17, v26
	ds_bpermute_b32 v26, v40, v17
	v_cvt_pk_bf16_f32 v60, v60, v61
	v_cvt_pk_bf16_f32 v61, v62, v63
	global_store_dwordx2 v[42:43], v[60:61], off offset:288
	s_waitcnt lgkmcnt(0)
	v_add_f32_e32 v17, v17, v26
	ds_bpermute_b32 v26, v41, v17
	s_and_saveexec_b64 s[8:9], vcc
	s_cbranch_execz .LBB0_812
	v_lshlrev_b64 v[24:25], 6, v[24:25]
	v_lshl_add_u64 v[24:25], s[10:11], 0, v[24:25]
	v_lshl_add_u64 v[24:25], s[52:53], 2, v[24:25]
	s_lshl_b32 s40, s82, 2
	v_lshl_add_u64 v[24:25], v[24:25], 0, s[40:41]
	s_waitcnt lgkmcnt(0)
	v_add_f32_e32 v17, v17, v26
	global_store_dword v[24:25], v17, off

; __device__ __forceinline__ unsigned pk2(float lo, float hi) { f32x2_t v = {lo, hi}; bf16x2_t b = __builtin_convertvector(v, bf16x2_t); return __builtin_bit_cast(unsigned, b); }
;     __device__ __forceinline__ void operator()(const f32x4 (&acc)[2][2][4][2], const Unit& u, int wr, int wc, int fr, int fq) const {
;     ...
;             for (int m = 0; m < 4; ++m) { const int row = row0 + ai * HALF + m * 16;
;                 const float* xr = (row < TP ? xp + (size_t)row * DM : xs + (size_t)(row - TP) * DM) + col0;
;                 bf16_t* brow = x1b + (size_t)row * DM + col0; float ss = 0.f;
; #pragma unroll
;                 for (int bj = 0; bj < 2; ++bj)
; #pragma unroll
;                     for (int n = 0; n < 2; ++n) { const int co = bj * HALF + n * 16; const f32x4 v = *(const f32x4*)(xr + co) + acc[ai][bj][m][n] * sc;
;                         u32x2 w; w.x = pk2(v[0], v[1]); w.y = pk2(v[2], v[3]); *(u32x2*)(brow + co) = w;
;                         ss += (v[0] * v[0] + v[1] * v[1]) + (v[2] * v[2] + v[3] * v[3]); }
;                 ss += __shfl_xor(ss, 16); ss += __shfl_xor(ss, 32);
;                 if (fq == 0) ssq[(size_t)row * 16 + u.pn * 4 + wc] = ss; }
.LBB0_816:
	s_or_b64 exec, exec, s[8:9]
	s_waitcnt lgkmcnt(0)
	v_lshl_add_u64 v[26:27], v[18:19], 2, v[26:27]
	global_load_dwordx4 v[60:63], v[26:27], off
	global_load_dwordx4 v[200:203], v[26:27], off offset:64
	global_load_dwordx4 v[204:207], v[26:27], off offset:512
	global_load_dwordx4 v[208:211], v[26:27], off offset:576
	v_lshlrev_b64 v[42:43], 11, v[24:25]
	v_lshl_add_u64 v[42:43], s[2:3], 0, v[42:43]
	v_lshl_add_u64 v[42:43], v[18:19], 1, v[42:43]
	s_waitcnt vmcnt(3)
	v_pk_add_f32 v[62:63], v[58:59], v[62:63]
	v_pk_add_f32 v[60:61], v[56:57], v[60:61]
	v_cvt_pk_bf16_f32 v57, v62, v63
	v_cvt_pk_bf16_f32 v56, v60, v61
	global_store_dwordx2 v[42:43], v[56:57], off
	s_waitcnt vmcnt(3)
	v_mov_b64_e32 v[56:57], v[200:201]
	v_mov_b64_e32 v[58:59], v[202:203]
	v_mul_f32_e32 v17, v61, v61
	v_fmac_f32_e32 v17, v60, v60
	v_pk_add_f32 v[58:59], v[50:51], v[58:59]
	v_pk_add_f32 v[56:57], v[48:49], v[56:57]
	v_cvt_pk_bf16_f32 v49, v58, v59
	v_cvt_pk_bf16_f32 v48, v56, v57
	global_store_dwordx2 v[42:43], v[48:49], off offset:32
	s_waitcnt vmcnt(3)
	v_mov_b64_e32 v[48:49], v[204:205]
	v_mov_b64_e32 v[50:51], v[206:207]
	v_pk_add_f32 v[54:55], v[54:55], v[50:51]
	v_pk_add_f32 v[52:53], v[52:53], v[48:49]
	v_cvt_pk_bf16_f32 v49, v54, v55
	v_cvt_pk_bf16_f32 v48, v52, v53
	global_store_dwordx2 v[42:43], v[48:49], off offset:256
	s_waitcnt vmcnt(3)
	v_mov_b64_e32 v[48:49], v[208:209]
	v_mov_b64_e32 v[50:51], v[210:211]
	v_mul_f32_e32 v26, v63, v63
	v_fmac_f32_e32 v26, v62, v62
	v_add_f32_e32 v17, v17, v26
	v_mul_f32_e32 v26, v57, v57
	v_mul_f32_e32 v27, v59, v59
	v_fmac_f32_e32 v26, v56, v56
	v_fmac_f32_e32 v27, v58, v58
	v_add_f32_e32 v26, v26, v27
	v_add_f32_e32 v17, v17, v26
	v_mul_f32_e32 v26, v53, v53
	v_mul_f32_e32 v27, v55, v55
	v_fmac_f32_e32 v26, v52, v52
	v_fmac_f32_e32 v27, v54, v54
	v_add_f32_e32 v26, v26, v27
	v_add_f32_e32 v17, v17, v26
	v_pk_add_f32 v[46:47], v[46:47], v[50:51]
	v_pk_add_f32 v[44:45], v[44:45], v[48:49]
	v_mul_f32_e32 v27, v47, v47
	v_mul_f32_e32 v26, v45, v45
	v_fmac_f32_e32 v26, v44, v44
	v_fmac_f32_e32 v27, v46, v46
	v_add_f32_e32 v26, v26, v27
	v_add_f32_e32 v17, v17, v26
	ds_bpermute_b32 v26, v40, v17
	v_cvt_pk_bf16_f32 v44, v44, v45
	v_cvt_pk_bf16_f32 v45, v46, v47
	global_store_dwordx2 v[42:43], v[44:45], off offset:288
	s_waitcnt lgkmcnt(0)
	v_add_f32_e32 v17, v17, v26
	ds_bpermute_b32 v26, v41, v17
	s_and_saveexec_b64 s[8:9], vcc
	s_cbranch_execz .LBB0_818
	v_lshlrev_b64 v[24:25], 6, v[24:25]
	v_lshl_add_u64 v[24:25], s[10:11], 0, v[24:25]
	v_lshl_add_u64 v[24:25], s[52:53], 2, v[24:25]
	s_lshl_b32 s40, s82, 2
	v_lshl_add_u64 v[24:25], v[24:25], 0, s[40:41]
	s_waitcnt lgkmcnt(0)
	v_add_f32_e32 v17, v17, v26
	global_store_dword v[24:25], v17, off

; __device__ __forceinline__ unsigned pk2(float lo, float hi) { f32x2_t v = {lo, hi}; bf16x2_t b = __builtin_convertvector(v, bf16x2_t); return __builtin_bit_cast(unsigned, b); }
;     __device__ __forceinline__ void operator()(const f32x4 (&acc)[2][2][4][2], const Unit& u, int wr, int wc, int fr, int fq) const {
;     ...
;             for (int m = 0; m < 4; ++m) { const int row = row0 + ai * HALF + m * 16;
;                 const float* xr = (row < TP ? xp + (size_t)row * DM : xs + (size_t)(row - TP) * DM) + col0;
;                 bf16_t* brow = x1b + (size_t)row * DM + col0; float ss = 0.f;
; #pragma unroll
;                 for (int bj = 0; bj < 2; ++bj)
; #pragma unroll
;                     for (int n = 0; n < 2; ++n) { const int co = bj * HALF + n * 16; const f32x4 v = *(const f32x4*)(xr + co) + acc[ai][bj][m][n] * sc;
;                         u32x2 w; w.x = pk2(v[0], v[1]); w.y = pk2(v[2], v[3]); *(u32x2*)(brow + co) = w;
;                         ss += (v[0] * v[0] + v[1] * v[1]) + (v[2] * v[2] + v[3] * v[3]); }
;                 ss += __shfl_xor(ss, 16); ss += __shfl_xor(ss, 32);
;                 if (fq == 0) ssq[(size_t)row * 16 + u.pn * 4 + wc] = ss; }
.LBB0_822:
	s_or_b64 exec, exec, s[8:9]
	s_waitcnt lgkmcnt(0)
	v_lshl_add_u64 v[46:47], v[18:19], 2, v[26:27]
	global_load_dwordx4 v[42:45], v[46:47], off
	global_load_dwordx4 v[200:203], v[46:47], off offset:64
	global_load_dwordx4 v[204:207], v[46:47], off offset:512
	global_load_dwordx4 v[208:211], v[46:47], off offset:576
	v_lshlrev_b64 v[26:27], 11, v[24:25]
	v_lshl_add_u64 v[26:27], s[2:3], 0, v[26:27]
	v_lshl_add_u64 v[48:49], v[18:19], 1, v[26:27]
	s_waitcnt vmcnt(3)
	v_pk_add_f32 v[44:45], v[38:39], v[44:45]
	v_pk_add_f32 v[42:43], v[36:37], v[42:43]
	v_cvt_pk_bf16_f32 v27, v44, v45
	v_cvt_pk_bf16_f32 v26, v42, v43
	global_store_dwordx2 v[48:49], v[26:27], off
	s_waitcnt vmcnt(3)
	v_mov_b64_e32 v[36:37], v[200:201]
	v_mov_b64_e32 v[38:39], v[202:203]
	v_mul_f32_e32 v17, v43, v43
	v_fmac_f32_e32 v17, v42, v42
	v_pk_add_f32 v[30:31], v[30:31], v[38:39]
	v_pk_add_f32 v[36:37], v[28:29], v[36:37]
	v_cvt_pk_bf16_f32 v27, v30, v31
	v_cvt_pk_bf16_f32 v26, v36, v37
	global_store_dwordx2 v[48:49], v[26:27], off offset:32
	s_waitcnt vmcnt(3)
	v_mov_b64_e32 v[26:27], v[204:205]
	v_mov_b64_e32 v[28:29], v[206:207]
	v_mul_f32_e32 v38, v45, v45
	v_mul_f32_e32 v37, v37, v37
	v_mul_f32_e32 v31, v31, v31
	v_fmac_f32_e32 v38, v44, v44
	v_fmac_f32_e32 v37, v36, v36
	v_fmac_f32_e32 v31, v30, v30
	v_add_f32_e32 v17, v17, v38
	v_add_f32_e32 v30, v37, v31
	v_add_f32_e32 v17, v17, v30
	v_pk_add_f32 v[34:35], v[34:35], v[28:29]
	v_pk_add_f32 v[32:33], v[32:33], v[26:27]
	v_cvt_pk_bf16_f32 v27, v34, v35
	v_cvt_pk_bf16_f32 v26, v32, v33
	global_store_dwordx2 v[48:49], v[26:27], off offset:256
	s_waitcnt vmcnt(3)
	v_mov_b64_e32 v[26:27], v[208:209]
	v_mov_b64_e32 v[28:29], v[210:211]
	v_mul_f32_e32 v30, v33, v33
	v_mul_f32_e32 v31, v35, v35
	v_fmac_f32_e32 v30, v32, v32
	v_fmac_f32_e32 v31, v34, v34
	v_add_f32_e32 v30, v30, v31
	v_add_f32_e32 v17, v17, v30
	v_pk_add_f32 v[22:23], v[22:23], v[28:29]
	v_pk_add_f32 v[26:27], v[20:21], v[26:27]
	v_mul_f32_e32 v21, v23, v23
	v_mul_f32_e32 v20, v27, v27
	v_fmac_f32_e32 v20, v26, v26
	v_fmac_f32_e32 v21, v22, v22
	v_add_f32_e32 v20, v20, v21
	v_add_f32_e32 v17, v17, v20
	ds_bpermute_b32 v20, v40, v17
	v_cvt_pk_bf16_f32 v26, v26, v27
	v_cvt_pk_bf16_f32 v27, v22, v23
	global_store_dwordx2 v[48:49], v[26:27], off offset:288
	s_waitcnt lgkmcnt(0)
	v_add_f32_e32 v17, v17, v20
	ds_bpermute_b32 v20, v41, v17
	s_and_saveexec_b64 s[8:9], vcc
	s_cbranch_execz .LBB0_824
	v_lshlrev_b64 v[22:23], 6, v[24:25]
	v_lshl_add_u64 v[22:23], s[10:11], 0, v[22:23]
	v_lshl_add_u64 v[22:23], s[52:53], 2, v[22:23]
	s_lshl_b32 s40, s82, 2
	v_lshl_add_u64 v[22:23], v[22:23], 0, s[40:41]
	s_waitcnt lgkmcnt(0)
	v_add_f32_e32 v17, v17, v20
	global_store_dword v[22:23], v17, off

; __device__ __forceinline__ unsigned pk2(float lo, float hi) { f32x2_t v = {lo, hi}; bf16x2_t b = __builtin_convertvector(v, bf16x2_t); return __builtin_bit_cast(unsigned, b); }
;     __device__ __forceinline__ void operator()(const f32x4 (&acc)[2][2][4][2], const Unit& u, int wr, int wc, int fr, int fq) const {
;     ...
;             for (int m = 0; m < 4; ++m) { const int row = row0 + ai * HALF + m * 16;
;                 const float* xr = (row < TP ? xp + (size_t)row * DM : xs + (size_t)(row - TP) * DM) + col0;
;                 bf16_t* brow = x1b + (size_t)row * DM + col0; float ss = 0.f;
; #pragma unroll
;                 for (int bj = 0; bj < 2; ++bj)
; #pragma unroll
;                     for (int n = 0; n < 2; ++n) { const int co = bj * HALF + n * 16; const f32x4 v = *(const f32x4*)(xr + co) + acc[ai][bj][m][n] * sc;
;                         u32x2 w; w.x = pk2(v[0], v[1]); w.y = pk2(v[2], v[3]); *(u32x2*)(brow + co) = w;
;                         ss += (v[0] * v[0] + v[1] * v[1]) + (v[2] * v[2] + v[3] * v[3]); }
;                 ss += __shfl_xor(ss, 16); ss += __shfl_xor(ss, 32);
;                 if (fq == 0) ssq[(size_t)row * 16 + u.pn * 4 + wc] = ss; }
.LBB0_828:
	s_or_b64 exec, exec, s[8:9]
	v_lshl_add_u64 v[16:17], v[18:19], 2, v[22:23]
	global_load_dwordx4 v[22:25], v[16:17], off
	global_load_dwordx4 v[200:203], v[16:17], off offset:64
	global_load_dwordx4 v[204:207], v[16:17], off offset:512
	global_load_dwordx4 v[208:211], v[16:17], off offset:576
	v_lshlrev_b64 v[26:27], 11, v[20:21]
	v_lshl_add_u64 v[26:27], s[2:3], 0, v[26:27]
	v_lshl_add_u64 v[18:19], v[18:19], 1, v[26:27]
	s_waitcnt vmcnt(3)
	v_pk_add_f32 v[24:25], v[14:15], v[24:25]
	v_pk_add_f32 v[22:23], v[12:13], v[22:23]
	v_cvt_pk_bf16_f32 v13, v24, v25
	v_cvt_pk_bf16_f32 v12, v22, v23
	global_store_dwordx2 v[18:19], v[12:13], off
	s_waitcnt vmcnt(3)
	v_mov_b64_e32 v[12:13], v[200:201]
	v_mov_b64_e32 v[14:15], v[202:203]
	v_pk_add_f32 v[14:15], v[10:11], v[14:15]
	v_pk_add_f32 v[12:13], v[8:9], v[12:13]
	v_cvt_pk_bf16_f32 v9, v14, v15
	v_cvt_pk_bf16_f32 v8, v12, v13
	global_store_dwordx2 v[18:19], v[8:9], off offset:32
	s_waitcnt vmcnt(3)
	v_mov_b64_e32 v[8:9], v[204:205]
	v_mov_b64_e32 v[10:11], v[206:207]
	v_mul_f32_e32 v13, v13, v13
	v_mul_f32_e32 v15, v15, v15
	v_fmac_f32_e32 v13, v12, v12
	v_fmac_f32_e32 v15, v14, v14
	v_add_f32_e32 v12, v13, v15
	v_pk_add_f32 v[10:11], v[6:7], v[10:11]
	v_pk_add_f32 v[8:9], v[4:5], v[8:9]
	v_cvt_pk_bf16_f32 v5, v10, v11
	v_cvt_pk_bf16_f32 v4, v8, v9
	global_store_dwordx2 v[18:19], v[4:5], off offset:256
	s_waitcnt vmcnt(3)
	v_mov_b64_e32 v[4:5], v[208:209]
	v_mov_b64_e32 v[6:7], v[210:211]
	v_mul_f32_e32 v16, v23, v23
	v_mul_f32_e32 v17, v25, v25
	v_fmac_f32_e32 v16, v22, v22
	v_fmac_f32_e32 v17, v24, v24
	v_mul_f32_e32 v9, v9, v9
	v_mul_f32_e32 v11, v11, v11
	v_add_f32_e32 v16, v16, v17
	v_fmac_f32_e32 v9, v8, v8
	v_fmac_f32_e32 v11, v10, v10
	v_add_f32_e32 v12, v16, v12
	v_add_f32_e32 v8, v9, v11
	v_add_f32_e32 v8, v12, v8
	v_pk_add_f32 v[2:3], v[2:3], v[6:7]
	v_pk_add_f32 v[4:5], v[0:1], v[4:5]
	v_mul_f32_e32 v1, v3, v3
	v_mul_f32_e32 v0, v5, v5
	v_fmac_f32_e32 v0, v4, v4
	v_fmac_f32_e32 v1, v2, v2
	v_add_f32_e32 v0, v0, v1
	v_add_f32_e32 v0, v8, v0
	ds_bpermute_b32 v1, v40, v0
	v_cvt_pk_bf16_f32 v4, v4, v5
	v_cvt_pk_bf16_f32 v5, v2, v3
	global_store_dwordx2 v[18:19], v[4:5], off offset:288
	s_waitcnt lgkmcnt(0)
	v_add_f32_e32 v0, v0, v1
	ds_bpermute_b32 v1, v41, v0
	s_and_saveexec_b64 s[8:9], vcc
	s_cbranch_execz .LBB0_830
	v_lshlrev_b64 v[2:3], 6, v[20:21]
	v_lshl_add_u64 v[2:3], s[10:11], 0, v[2:3]
	v_lshl_add_u64 v[2:3], s[52:53], 2, v[2:3]
	s_lshl_b32 s40, s82, 2
	v_lshl_add_u64 v[2:3], v[2:3], 0, s[40:41]
	s_waitcnt lgkmcnt(0)
	v_add_f32_e32 v0, v0, v1
	global_store_dword v[2:3], v0, off

;     __device__ __forceinline__ void operator()(f32x4 (&acc)[2][2][4][2], const Unit& u, int wr, int wc, int fr, int fq) const {
;     ...
;         for (int ai = 0; ai < 2; ++ai)
; #pragma unroll
;             for (int m = 0; m < 4; ++m) { const int row = row0 + ai * HALF + m * 16; float* orow = out + (size_t)row * DM + col0;
;                 const unsigned long long* sp = (const unsigned long long*)(xbuf + (size_t)row * 16 + 4 * fq);
;                 const unsigned long long qa = __hip_atomic_load(sp, __ATOMIC_RELAXED, __HIP_MEMORY_SCOPE_AGENT), qb = __hip_atomic_load(sp + 1, __ATOMIC_RELAXED, __HIP_MEMORY_SCOPE_AGENT);
;                 float t = (__uint_as_float((unsigned)qa) + __uint_as_float((unsigned)(qa >> 32))) + (__uint_as_float((unsigned)qb) + __uint_as_float((unsigned)(qb >> 32)));
;                 t += __shfl_xor(t, 16); t += __shfl_xor(t, 32);
;                 const float rs = rsqrtf(t * (1.0f / DM) + EPS);
; #pragma unroll
;                 for (int bj = 0; bj < 2; ++bj)
; #pragma unroll
;                     for (int n = 0; n < 2; ++n) { const int co = bj * HALF + n * 16; const f32x4 g = *(const f32x4*)(gf + col0 + co); *(f32x4*)(orow + co) = acc[ai][bj][m][n] * rs * g; } }
.LBB0_994:
	v_ashrrev_i32_e32 v139, 31, v138
	v_lshlrev_b64 v[170:171], 2, v[138:139]
	v_lshl_add_u64 v[138:139], v[144:145], 0, v[170:171]
	global_load_dwordx2 v[144:145], v[138:139], off sc1
	global_load_dwordx2 v[190:191], v[138:139], off offset:8 sc1
	v_readlane_b32 s56, v249, 49
	v_readlane_b32 s58, v249, 51
	v_readlane_b32 s59, v249, 52
	v_lshlrev_b64 v[138:139], 2, v[136:137]
	s_mov_b64 s[46:47], s[58:59]
	v_lshl_add_u64 v[136:137], s[46:47], 0, v[138:139]
	global_load_dwordx4 v[212:215], v[136:137], off
	global_load_dwordx4 v[216:219], v[136:137], off offset:64
	global_load_dwordx4 v[220:223], v[136:137], off offset:512
	global_load_dwordx4 v[224:227], v[136:137], off offset:576
	v_readlane_b32 s60, v249, 53
	v_readlane_b32 s61, v249, 54
	s_mov_b64 s[48:49], s[60:61]
	v_lshlrev_b64 v[134:135], 12, v[134:135]
	v_lshl_add_u64 v[134:135], s[48:49], 0, v[134:135]
	v_lshl_add_u64 v[134:135], v[134:135], 0, v[138:139]
	v_lshlrev_b64 v[100:101], 12, v[100:101]
	v_lshl_add_u64 v[100:101], s[48:49], 0, v[100:101]
	v_lshl_add_u64 v[100:101], v[100:101], 0, v[138:139]
	v_lshlrev_b64 v[84:85], 12, v[84:85]
	v_lshl_add_u64 v[84:85], s[48:49], 0, v[84:85]
	v_lshl_add_u64 v[84:85], v[84:85], 0, v[138:139]
	v_lshlrev_b64 v[68:69], 12, v[68:69]
	v_lshl_add_u64 v[68:69], s[48:49], 0, v[68:69]
	v_lshl_add_u64 v[68:69], v[68:69], 0, v[138:139]
	v_lshlrev_b64 v[52:53], 12, v[52:53]
	v_lshl_add_u64 v[52:53], s[48:49], 0, v[52:53]
	v_lshl_add_u64 v[52:53], v[52:53], 0, v[138:139]
	v_lshlrev_b64 v[36:37], 12, v[36:37]
	v_lshl_add_u64 v[36:37], s[48:49], 0, v[36:37]
	v_lshl_add_u64 v[36:37], v[36:37], 0, v[138:139]
	v_lshlrev_b64 v[20:21], 12, v[20:21]
	v_lshl_add_u64 v[20:21], s[48:49], 0, v[20:21]
	v_lshl_add_u64 v[20:21], v[20:21], 0, v[138:139]
	v_readlane_b32 s57, v249, 50
	v_readlane_b32 s62, v249, 55
	v_readlane_b32 s63, v249, 56
	s_waitcnt vmcnt(5)
	v_add_f32_e32 v144, v144, v145
	s_waitcnt vmcnt(4)
	v_add_f32_e32 v145, v190, v191
	v_add_f32_e32 v144, v144, v145
	ds_bpermute_b32 v145, v128, v144
	s_waitcnt lgkmcnt(0)
	v_add_f32_e32 v144, v144, v145
	ds_bpermute_b32 v145, v184, v144
	s_waitcnt lgkmcnt(0)
	v_add_f32_e32 v144, v144, v145
	v_fmamk_f32 v144, v144, 0x3a800000, v183
	v_mul_f32_e32 v145, 0x4b800000, v144
	v_cmp_gt_f32_e32 vcc, s42, v144
	s_nop 1
	v_cndmask_b32_e32 v144, v144, v145, vcc
	v_rsq_f32_e32 v144, v144
	s_nop 0
	v_mul_f32_e32 v145, 0x45800000, v144
	v_cndmask_b32_e32 v144, v144, v145, vcc
	v_pk_mul_f32 v[140:141], v[140:141], v[144:145] op_sel_hi:[1,0]
	v_pk_mul_f32 v[126:127], v[126:127], v[144:145] op_sel_hi:[1,0]
	s_waitcnt vmcnt(0)
	s_nop 1
	v_mov_b64_e32 v[186:187], v[212:213]
	v_mov_b64_e32 v[188:189], v[214:215]
	v_pk_mul_f32 v[186:187], v[186:187], v[140:141]
	v_pk_mul_f32 v[188:189], v[188:189], v[126:127]
	global_store_dwordx4 v[134:135], v[186:189], off
	s_nop 1
	v_mov_b64_e32 v[186:187], v[216:217]
	v_mov_b64_e32 v[188:189], v[218:219]
	v_pk_mul_f32 v[126:127], v[122:123], v[144:145] op_sel_hi:[1,0]
	v_pk_mul_f32 v[122:123], v[124:125], v[144:145] op_sel_hi:[1,0]
	v_pk_mul_f32 v[118:119], v[118:119], v[144:145] op_sel_hi:[1,0]
	v_pk_mul_f32 v[116:117], v[116:117], v[144:145] op_sel_hi:[1,0]
	v_pk_mul_f32 v[114:115], v[114:115], v[144:145] op_sel_hi:[1,0]
	v_pk_mul_f32 v[112:113], v[112:113], v[144:145] op_sel_hi:[1,0]
	v_pk_mul_f32 v[122:123], v[186:187], v[122:123]
	v_pk_mul_f32 v[124:125], v[188:189], v[126:127]
	global_store_dwordx4 v[134:135], v[122:125], off offset:64
	s_nop 1
	v_mov_b64_e32 v[122:123], v[220:221]
	v_mov_b64_e32 v[124:125], v[222:223]
	v_pk_mul_f32 v[116:117], v[122:123], v[116:117]
	v_pk_mul_f32 v[118:119], v[124:125], v[118:119]
	global_store_dwordx4 v[134:135], v[116:119], off offset:512
	s_nop 1
	v_mov_b64_e32 v[116:117], v[224:225]
	v_mov_b64_e32 v[118:119], v[226:227]
	v_lshl_add_u64 v[122:123], v[148:149], 0, v[170:171]
	v_pk_mul_f32 v[112:113], v[116:117], v[112:113]
	v_pk_mul_f32 v[114:115], v[118:119], v[114:115]
	global_store_dwordx4 v[134:135], v[112:115], off offset:576
	global_load_dwordx2 v[116:117], v[122:123], off sc1
	global_load_dwordx2 v[118:119], v[122:123], off offset:8 sc1
	s_nop 0
	s_nop 1
	v_mov_b64_e32 v[112:113], v[212:213]
	v_mov_b64_e32 v[114:115], v[214:215]
	s_waitcnt vmcnt(1)
	v_add_f32_e32 v116, v116, v117
	s_waitcnt vmcnt(0)
	v_add_f32_e32 v117, v118, v119
	v_add_f32_e32 v116, v116, v117
	ds_bpermute_b32 v117, v128, v116
	s_waitcnt lgkmcnt(0)
	v_add_f32_e32 v116, v116, v117
	ds_bpermute_b32 v117, v184, v116
	s_waitcnt lgkmcnt(0)
	v_add_f32_e32 v116, v116, v117
	v_fmamk_f32 v116, v116, 0x3a800000, v183
	v_mul_f32_e32 v117, 0x4b800000, v116
	v_cmp_gt_f32_e32 vcc, s42, v116
	s_nop 1
	v_cndmask_b32_e32 v116, v116, v117, vcc
	v_rsq_f32_e32 v118, v116
	v_lshlrev_b64 v[116:117], 12, v[120:121]
	v_lshl_add_u64 v[116:117], s[48:49], 0, v[116:117]
	v_lshl_add_u64 v[116:117], v[116:117], 0, v[138:139]
	v_mul_f32_e32 v119, 0x45800000, v118
	v_cndmask_b32_e32 v118, v118, v119, vcc
	v_pk_mul_f32 v[120:121], v[142:143], v[118:119] op_sel_hi:[1,0]
	v_pk_mul_f32 v[110:111], v[110:111], v[118:119] op_sel_hi:[1,0]
	v_pk_mul_f32 v[112:113], v[112:113], v[120:121]
	v_pk_mul_f32 v[114:115], v[114:115], v[110:111]
	global_store_dwordx4 v[116:117], v[112:115], off
	s_nop 1
	v_mov_b64_e32 v[110:111], v[216:217]
	v_mov_b64_e32 v[112:113], v[218:219]
	v_pk_mul_f32 v[98:99], v[98:99], v[118:119] op_sel_hi:[1,0]
	v_pk_mul_f32 v[114:115], v[106:107], v[118:119] op_sel_hi:[1,0]
	v_pk_mul_f32 v[106:107], v[108:109], v[118:119] op_sel_hi:[1,0]
	v_pk_mul_f32 v[96:97], v[96:97], v[118:119] op_sel_hi:[1,0]
	v_pk_mul_f32 v[106:107], v[110:111], v[106:107]
	v_pk_mul_f32 v[108:109], v[112:113], v[114:115]
	global_store_dwordx4 v[116:117], v[106:109], off offset:64
	s_nop 1
	v_mov_b64_e32 v[106:107], v[220:221]
	v_mov_b64_e32 v[108:109], v[222:223]
	v_pk_mul_f32 v[110:111], v[102:103], v[118:119] op_sel_hi:[1,0]
	v_pk_mul_f32 v[102:103], v[104:105], v[118:119] op_sel_hi:[1,0]
	v_pk_mul_f32 v[104:105], v[108:109], v[110:111]
	v_pk_mul_f32 v[102:103], v[106:107], v[102:103]
	global_store_dwordx4 v[116:117], v[102:105], off offset:512
	s_nop 1
	v_mov_b64_e32 v[102:103], v[224:225]
	v_mov_b64_e32 v[104:105], v[226:227]
	v_lshl_add_u64 v[106:107], v[152:153], 0, v[170:171]
	v_pk_mul_f32 v[96:97], v[102:103], v[96:97]
	v_pk_mul_f32 v[98:99], v[104:105], v[98:99]
	global_store_dwordx4 v[116:117], v[96:99], off offset:576
	global_load_dwordx2 v[102:103], v[106:107], off sc1
	global_load_dwordx2 v[104:105], v[106:107], off offset:8 sc1
	s_nop 0
	s_nop 1
	v_mov_b64_e32 v[96:97], v[212:213]
	v_mov_b64_e32 v[98:99], v[214:215]
	s_waitcnt vmcnt(1)
;     __device__ __forceinline__ void operator()(f32x4 (&acc)[2][2][4][2], const Unit& u, int wr, int wc, int fr, int fq) const {
;     ...
;         for (int ai = 0; ai < 2; ++ai)
; #pragma unroll
;             for (int m = 0; m < 4; ++m) { const int row = row0 + ai * HALF + m * 16; float* orow = out + (size_t)row * DM + col0;
;                 const unsigned long long* sp = (const unsigned long long*)(xbuf + (size_t)row * 16 + 4 * fq);
;                 const unsigned long long qa = __hip_atomic_load(sp, __ATOMIC_RELAXED, __HIP_MEMORY_SCOPE_AGENT), qb = __hip_atomic_load(sp + 1, __ATOMIC_RELAXED, __HIP_MEMORY_SCOPE_AGENT);
;                 float t = (__uint_as_float((unsigned)qa) + __uint_as_float((unsigned)(qa >> 32))) + (__uint_as_float((unsigned)qb) + __uint_as_float((unsigned)(qb >> 32)));
;                 t += __shfl_xor(t, 16); t += __shfl_xor(t, 32);
;                 const float rs = rsqrtf(t * (1.0f / DM) + EPS);
; #pragma unroll
;                 for (int bj = 0; bj < 2; ++bj)
; #pragma unroll
;                     for (int n = 0; n < 2; ++n) { const int co = bj * HALF + n * 16; const f32x4 g = *(const f32x4*)(gf + col0 + co); *(f32x4*)(orow + co) = acc[ai][bj][m][n] * rs * g; } }
	v_add_f32_e32 v102, v102, v103
	s_waitcnt vmcnt(0)
	v_add_f32_e32 v103, v104, v105
	v_add_f32_e32 v102, v102, v103
	ds_bpermute_b32 v103, v128, v102
	s_waitcnt lgkmcnt(0)
	v_add_f32_e32 v102, v102, v103
	ds_bpermute_b32 v103, v184, v102
	s_waitcnt lgkmcnt(0)
	v_add_f32_e32 v102, v102, v103
	v_fmamk_f32 v102, v102, 0x3a800000, v183
	v_mul_f32_e32 v103, 0x4b800000, v102
	v_cmp_gt_f32_e32 vcc, s42, v102
	s_nop 1
	v_cndmask_b32_e32 v102, v102, v103, vcc
	v_rsq_f32_e32 v102, v102
	s_nop 0
	v_mul_f32_e32 v103, 0x45800000, v102
	v_cndmask_b32_e32 v102, v102, v103, vcc
	v_pk_mul_f32 v[104:105], v[146:147], v[102:103] op_sel_hi:[1,0]
	v_pk_mul_f32 v[94:95], v[94:95], v[102:103] op_sel_hi:[1,0]
	v_pk_mul_f32 v[96:97], v[96:97], v[104:105]
	v_pk_mul_f32 v[98:99], v[98:99], v[94:95]
	global_store_dwordx4 v[100:101], v[96:99], off
	s_nop 1
	v_mov_b64_e32 v[94:95], v[216:217]
	v_mov_b64_e32 v[96:97], v[218:219]
	v_pk_mul_f32 v[82:83], v[82:83], v[102:103] op_sel_hi:[1,0]
	v_pk_mul_f32 v[98:99], v[90:91], v[102:103] op_sel_hi:[1,0]
	v_pk_mul_f32 v[90:91], v[92:93], v[102:103] op_sel_hi:[1,0]
	v_pk_mul_f32 v[80:81], v[80:81], v[102:103] op_sel_hi:[1,0]
	v_pk_mul_f32 v[90:91], v[94:95], v[90:91]
	v_pk_mul_f32 v[92:93], v[96:97], v[98:99]
	global_store_dwordx4 v[100:101], v[90:93], off offset:64
	s_nop 1
	v_mov_b64_e32 v[90:91], v[220:221]
	v_mov_b64_e32 v[92:93], v[222:223]
	v_pk_mul_f32 v[94:95], v[86:87], v[102:103] op_sel_hi:[1,0]
	v_pk_mul_f32 v[86:87], v[88:89], v[102:103] op_sel_hi:[1,0]
	v_pk_mul_f32 v[88:89], v[92:93], v[94:95]
	v_pk_mul_f32 v[86:87], v[90:91], v[86:87]
	global_store_dwordx4 v[100:101], v[86:89], off offset:512
	s_nop 1
	v_mov_b64_e32 v[86:87], v[224:225]
	v_mov_b64_e32 v[88:89], v[226:227]
	v_lshl_add_u64 v[90:91], v[156:157], 0, v[170:171]
	v_pk_mul_f32 v[80:81], v[86:87], v[80:81]
	v_pk_mul_f32 v[82:83], v[88:89], v[82:83]
	global_store_dwordx4 v[100:101], v[80:83], off offset:576
	global_load_dwordx2 v[86:87], v[90:91], off sc1
	global_load_dwordx2 v[88:89], v[90:91], off offset:8 sc1
	s_nop 0
	s_nop 1
	v_mov_b64_e32 v[80:81], v[212:213]
	v_mov_b64_e32 v[82:83], v[214:215]
	s_waitcnt vmcnt(1)
	v_add_f32_e32 v86, v86, v87
	s_waitcnt vmcnt(0)
	v_add_f32_e32 v87, v88, v89
	v_add_f32_e32 v86, v86, v87
	ds_bpermute_b32 v87, v128, v86
	s_waitcnt lgkmcnt(0)
	v_add_f32_e32 v86, v86, v87
	ds_bpermute_b32 v87, v184, v86
	s_waitcnt lgkmcnt(0)
	v_add_f32_e32 v86, v86, v87
	v_fmamk_f32 v86, v86, 0x3a800000, v183
	v_mul_f32_e32 v87, 0x4b800000, v86
	v_cmp_gt_f32_e32 vcc, s42, v86
	s_nop 1
	v_cndmask_b32_e32 v86, v86, v87, vcc
	v_rsq_f32_e32 v86, v86
	s_nop 0
	v_mul_f32_e32 v87, 0x45800000, v86
	v_cndmask_b32_e32 v86, v86, v87, vcc
	v_pk_mul_f32 v[88:89], v[150:151], v[86:87] op_sel_hi:[1,0]
	v_pk_mul_f32 v[78:79], v[78:79], v[86:87] op_sel_hi:[1,0]
	v_pk_mul_f32 v[80:81], v[80:81], v[88:89]
	v_pk_mul_f32 v[82:83], v[82:83], v[78:79]
	global_store_dwordx4 v[84:85], v[80:83], off
	s_nop 1
	v_mov_b64_e32 v[78:79], v[216:217]
	v_mov_b64_e32 v[80:81], v[218:219]
	v_pk_mul_f32 v[66:67], v[66:67], v[86:87] op_sel_hi:[1,0]
	v_pk_mul_f32 v[82:83], v[74:75], v[86:87] op_sel_hi:[1,0]
	v_pk_mul_f32 v[74:75], v[76:77], v[86:87] op_sel_hi:[1,0]
	v_pk_mul_f32 v[64:65], v[64:65], v[86:87] op_sel_hi:[1,0]
	v_pk_mul_f32 v[74:75], v[78:79], v[74:75]
	v_pk_mul_f32 v[76:77], v[80:81], v[82:83]
	global_store_dwordx4 v[84:85], v[74:77], off offset:64
	s_nop 1
	v_mov_b64_e32 v[74:75], v[220:221]
	v_mov_b64_e32 v[76:77], v[222:223]
	v_pk_mul_f32 v[78:79], v[70:71], v[86:87] op_sel_hi:[1,0]
	v_pk_mul_f32 v[70:71], v[72:73], v[86:87] op_sel_hi:[1,0]
	v_pk_mul_f32 v[72:73], v[76:77], v[78:79]
	v_pk_mul_f32 v[70:71], v[74:75], v[70:71]
	global_store_dwordx4 v[84:85], v[70:73], off offset:512
	s_nop 1
	v_mov_b64_e32 v[70:71], v[224:225]
	v_mov_b64_e32 v[72:73], v[226:227]
	v_lshl_add_u64 v[74:75], v[160:161], 0, v[170:171]
	v_pk_mul_f32 v[64:65], v[70:71], v[64:65]
	v_pk_mul_f32 v[66:67], v[72:73], v[66:67]
	global_store_dwordx4 v[84:85], v[64:67], off offset:576
	global_load_dwordx2 v[70:71], v[74:75], off sc1
	global_load_dwordx2 v[72:73], v[74:75], off offset:8 sc1
	s_nop 0
	s_nop 1
	v_mov_b64_e32 v[64:65], v[212:213]
	v_mov_b64_e32 v[66:67], v[214:215]
	s_waitcnt vmcnt(1)
	v_add_f32_e32 v70, v70, v71
	s_waitcnt vmcnt(0)
	v_add_f32_e32 v71, v72, v73
	v_add_f32_e32 v70, v70, v71
	ds_bpermute_b32 v71, v128, v70
	s_waitcnt lgkmcnt(0)
	v_add_f32_e32 v70, v70, v71
	ds_bpermute_b32 v71, v184, v70
	s_waitcnt lgkmcnt(0)
	v_add_f32_e32 v70, v70, v71
	v_fmamk_f32 v70, v70, 0x3a800000, v183
	v_mul_f32_e32 v71, 0x4b800000, v70
	v_cmp_gt_f32_e32 vcc, s42, v70
	s_nop 1
	v_cndmask_b32_e32 v70, v70, v71, vcc
	v_rsq_f32_e32 v70, v70
	s_nop 0
	v_mul_f32_e32 v71, 0x45800000, v70
	v_cndmask_b32_e32 v70, v70, v71, vcc
	v_pk_mul_f32 v[72:73], v[154:155], v[70:71] op_sel_hi:[1,0]
	v_pk_mul_f32 v[62:63], v[62:63], v[70:71] op_sel_hi:[1,0]
	v_pk_mul_f32 v[64:65], v[64:65], v[72:73]
	v_pk_mul_f32 v[66:67], v[66:67], v[62:63]
	global_store_dwordx4 v[68:69], v[64:67], off
	s_nop 1
	v_mov_b64_e32 v[62:63], v[216:217]
	v_mov_b64_e32 v[64:65], v[218:219]
	v_pk_mul_f32 v[50:51], v[50:51], v[70:71] op_sel_hi:[1,0]
	v_pk_mul_f32 v[66:67], v[58:59], v[70:71] op_sel_hi:[1,0]
	v_pk_mul_f32 v[58:59], v[60:61], v[70:71] op_sel_hi:[1,0]
	v_pk_mul_f32 v[48:49], v[48:49], v[70:71] op_sel_hi:[1,0]
	v_pk_mul_f32 v[58:59], v[62:63], v[58:59]
	v_pk_mul_f32 v[60:61], v[64:65], v[66:67]
	global_store_dwordx4 v[68:69], v[58:61], off offset:64
	s_nop 1
	v_mov_b64_e32 v[58:59], v[220:221]
	v_mov_b64_e32 v[60:61], v[222:223]
	v_pk_mul_f32 v[62:63], v[54:55], v[70:71] op_sel_hi:[1,0]
	v_pk_mul_f32 v[54:55], v[56:57], v[70:71] op_sel_hi:[1,0]
	v_pk_mul_f32 v[56:57], v[60:61], v[62:63]
	v_pk_mul_f32 v[54:55], v[58:59], v[54:55]
	global_store_dwordx4 v[68:69], v[54:57], off offset:512
	s_nop 1
	v_mov_b64_e32 v[54:55], v[224:225]
	v_mov_b64_e32 v[56:57], v[226:227]
	v_lshl_add_u64 v[58:59], v[164:165], 0, v[170:171]
	v_pk_mul_f32 v[48:49], v[54:55], v[48:49]
	v_pk_mul_f32 v[50:51], v[56:57], v[50:51]
	global_store_dwordx4 v[68:69], v[48:51], off offset:576
	global_load_dwordx2 v[54:55], v[58:59], off sc1
	global_load_dwordx2 v[56:57], v[58:59], off offset:8 sc1
	s_nop 0
	s_nop 1
	v_mov_b64_e32 v[48:49], v[212:213]
	v_mov_b64_e32 v[50:51], v[214:215]
	s_waitcnt vmcnt(1)
; #define PG8_BAR __builtin_amdgcn_s_barrier()
;     __device__ __forceinline__ void operator()(f32x4 (&acc)[2][2][4][2], const Unit& u, int wr, int wc, int fr, int fq) const {
;     ...
;         for (int ai = 0; ai < 2; ++ai)
; #pragma unroll
;             for (int m = 0; m < 4; ++m) { const int row = row0 + ai * HALF + m * 16; float* orow = out + (size_t)row * DM + col0;
;                 const unsigned long long* sp = (const unsigned long long*)(xbuf + (size_t)row * 16 + 4 * fq);
;                 const unsigned long long qa = __hip_atomic_load(sp, __ATOMIC_RELAXED, __HIP_MEMORY_SCOPE_AGENT), qb = __hip_atomic_load(sp + 1, __ATOMIC_RELAXED, __HIP_MEMORY_SCOPE_AGENT);
;                 float t = (__uint_as_float((unsigned)qa) + __uint_as_float((unsigned)(qa >> 32))) + (__uint_as_float((unsigned)qb) + __uint_as_float((unsigned)(qb >> 32)));
;                 t += __shfl_xor(t, 16); t += __shfl_xor(t, 32);
;                 const float rs = rsqrtf(t * (1.0f / DM) + EPS);
; #pragma unroll
;                 for (int bj = 0; bj < 2; ++bj)
; #pragma unroll
;                     for (int n = 0; n < 2; ++n) { const int co = bj * HALF + n * 16; const f32x4 g = *(const f32x4*)(gf + col0 + co); *(f32x4*)(orow + co) = acc[ai][bj][m][n] * rs * g; } }
; template <class Epi, class SchedT, bool ALIGN_EPI, bool SP2, bool FP8 = false>
; __device__ __forceinline__ void gemm_phase(LAS unsigned char* lds, const Gemm g, const SchedT& S, const Epi& E, const int wid) {
;     ...
;         if (!has_next) break;
; #pragma unroll
;         for (int a = 0; a < 2; ++a)
; #pragma unroll
;             for (int b = 0; b < 2; ++b)
; #pragma unroll
;                 for (int m = 0; m < 4; ++m)
; #pragma unroll
;                     for (int n = 0; n < 2; ++n) acc[a][b][m][n] = (f32x4){0.f, 0.f, 0.f, 0.f};
;         cur = nxt; cA = nA; cB = nB; ++ui;
;         if constexpr (ALIGN_EPI) { if (wr == 1) PG8_BAR; }
	v_add_f32_e32 v54, v54, v55
	s_waitcnt vmcnt(0)
	v_add_f32_e32 v55, v56, v57
	v_add_f32_e32 v54, v54, v55
	ds_bpermute_b32 v55, v128, v54
	s_waitcnt lgkmcnt(0)
	v_add_f32_e32 v54, v54, v55
	ds_bpermute_b32 v55, v184, v54
	s_waitcnt lgkmcnt(0)
	v_add_f32_e32 v54, v54, v55
	v_fmamk_f32 v54, v54, 0x3a800000, v183
	v_mul_f32_e32 v55, 0x4b800000, v54
	v_cmp_gt_f32_e32 vcc, s42, v54
	s_nop 1
	v_cndmask_b32_e32 v54, v54, v55, vcc
	v_rsq_f32_e32 v54, v54
	s_nop 0
	v_mul_f32_e32 v55, 0x45800000, v54
	v_cndmask_b32_e32 v54, v54, v55, vcc
	v_pk_mul_f32 v[56:57], v[158:159], v[54:55] op_sel_hi:[1,0]
	v_pk_mul_f32 v[46:47], v[46:47], v[54:55] op_sel_hi:[1,0]
	v_pk_mul_f32 v[48:49], v[48:49], v[56:57]
	v_pk_mul_f32 v[50:51], v[50:51], v[46:47]
	global_store_dwordx4 v[52:53], v[48:51], off
	s_nop 1
	v_mov_b64_e32 v[46:47], v[216:217]
	v_mov_b64_e32 v[48:49], v[218:219]
	v_pk_mul_f32 v[34:35], v[34:35], v[54:55] op_sel_hi:[1,0]
	v_pk_mul_f32 v[50:51], v[42:43], v[54:55] op_sel_hi:[1,0]
	v_pk_mul_f32 v[42:43], v[44:45], v[54:55] op_sel_hi:[1,0]
	v_pk_mul_f32 v[32:33], v[32:33], v[54:55] op_sel_hi:[1,0]
	v_pk_mul_f32 v[42:43], v[46:47], v[42:43]
	v_pk_mul_f32 v[44:45], v[48:49], v[50:51]
	global_store_dwordx4 v[52:53], v[42:45], off offset:64
	s_nop 1
	v_mov_b64_e32 v[42:43], v[220:221]
	v_mov_b64_e32 v[44:45], v[222:223]
	v_pk_mul_f32 v[46:47], v[38:39], v[54:55] op_sel_hi:[1,0]
	v_pk_mul_f32 v[38:39], v[40:41], v[54:55] op_sel_hi:[1,0]
	v_pk_mul_f32 v[40:41], v[44:45], v[46:47]
	v_pk_mul_f32 v[38:39], v[42:43], v[38:39]
	global_store_dwordx4 v[52:53], v[38:41], off offset:512
	s_nop 1
	v_mov_b64_e32 v[38:39], v[224:225]
	v_mov_b64_e32 v[40:41], v[226:227]
	v_lshl_add_u64 v[42:43], v[166:167], 0, v[170:171]
	v_pk_mul_f32 v[32:33], v[38:39], v[32:33]
	v_pk_mul_f32 v[34:35], v[40:41], v[34:35]
	global_store_dwordx4 v[52:53], v[32:35], off offset:576
	global_load_dwordx2 v[38:39], v[42:43], off sc1
	global_load_dwordx2 v[40:41], v[42:43], off offset:8 sc1
	s_nop 0
	s_nop 1
	v_mov_b64_e32 v[32:33], v[212:213]
	v_mov_b64_e32 v[34:35], v[214:215]
	s_waitcnt vmcnt(1)
	v_add_f32_e32 v38, v38, v39
	s_waitcnt vmcnt(0)
	v_add_f32_e32 v39, v40, v41
	v_add_f32_e32 v38, v38, v39
	ds_bpermute_b32 v39, v128, v38
	s_waitcnt lgkmcnt(0)
	v_add_f32_e32 v38, v38, v39
	ds_bpermute_b32 v39, v184, v38
	s_waitcnt lgkmcnt(0)
	v_add_f32_e32 v38, v38, v39
	v_fmamk_f32 v38, v38, 0x3a800000, v183
	v_mul_f32_e32 v39, 0x4b800000, v38
	v_cmp_gt_f32_e32 vcc, s42, v38
	s_nop 1
	v_cndmask_b32_e32 v38, v38, v39, vcc
	v_rsq_f32_e32 v38, v38
	s_nop 0
	v_mul_f32_e32 v39, 0x45800000, v38
	v_cndmask_b32_e32 v38, v38, v39, vcc
	v_pk_mul_f32 v[40:41], v[162:163], v[38:39] op_sel_hi:[1,0]
	v_pk_mul_f32 v[30:31], v[30:31], v[38:39] op_sel_hi:[1,0]
	v_pk_mul_f32 v[32:33], v[32:33], v[40:41]
	v_pk_mul_f32 v[34:35], v[34:35], v[30:31]
	global_store_dwordx4 v[36:37], v[32:35], off
	s_nop 1
	v_mov_b64_e32 v[30:31], v[216:217]
	v_mov_b64_e32 v[32:33], v[218:219]
	v_pk_mul_f32 v[18:19], v[18:19], v[38:39] op_sel_hi:[1,0]
	v_pk_mul_f32 v[34:35], v[26:27], v[38:39] op_sel_hi:[1,0]
	v_pk_mul_f32 v[26:27], v[28:29], v[38:39] op_sel_hi:[1,0]
	v_pk_mul_f32 v[16:17], v[16:17], v[38:39] op_sel_hi:[1,0]
	v_pk_mul_f32 v[26:27], v[30:31], v[26:27]
	v_pk_mul_f32 v[28:29], v[32:33], v[34:35]
	global_store_dwordx4 v[36:37], v[26:29], off offset:64
	s_nop 1
	v_mov_b64_e32 v[26:27], v[220:221]
	v_mov_b64_e32 v[28:29], v[222:223]
	v_pk_mul_f32 v[30:31], v[22:23], v[38:39] op_sel_hi:[1,0]
	v_pk_mul_f32 v[22:23], v[24:25], v[38:39] op_sel_hi:[1,0]
	v_pk_mul_f32 v[24:25], v[28:29], v[30:31]
	v_pk_mul_f32 v[22:23], v[26:27], v[22:23]
	global_store_dwordx4 v[36:37], v[22:25], off offset:512
	s_nop 1
	v_mov_b64_e32 v[22:23], v[224:225]
	v_mov_b64_e32 v[24:25], v[226:227]
	v_lshl_add_u64 v[26:27], v[168:169], 0, v[170:171]
	v_pk_mul_f32 v[16:17], v[22:23], v[16:17]
	v_pk_mul_f32 v[18:19], v[24:25], v[18:19]
	global_store_dwordx4 v[36:37], v[16:19], off offset:576
	global_load_dwordx2 v[22:23], v[26:27], off sc1
	global_load_dwordx2 v[24:25], v[26:27], off offset:8 sc1
	s_nop 0
	s_nop 1
	v_mov_b64_e32 v[16:17], v[212:213]
	v_mov_b64_e32 v[18:19], v[214:215]
	s_waitcnt vmcnt(1)
	v_add_f32_e32 v22, v22, v23
	s_waitcnt vmcnt(0)
	v_add_f32_e32 v23, v24, v25
	v_add_f32_e32 v22, v22, v23
	ds_bpermute_b32 v23, v128, v22
	s_waitcnt lgkmcnt(0)
	v_add_f32_e32 v22, v22, v23
	ds_bpermute_b32 v23, v184, v22
	s_waitcnt lgkmcnt(0)
	v_add_f32_e32 v22, v22, v23
	v_fmamk_f32 v22, v22, 0x3a800000, v183
	v_mul_f32_e32 v23, 0x4b800000, v22
	v_cmp_gt_f32_e32 vcc, s42, v22
	s_nop 1
	v_cndmask_b32_e32 v22, v22, v23, vcc
	v_rsq_f32_e32 v22, v22
	s_nop 0
	v_mul_f32_e32 v23, 0x45800000, v22
	v_cndmask_b32_e32 v22, v22, v23, vcc
	v_pk_mul_f32 v[12:13], v[12:13], v[22:23] op_sel_hi:[1,0]
	v_pk_mul_f32 v[14:15], v[14:15], v[22:23] op_sel_hi:[1,0]
	v_pk_mul_f32 v[12:13], v[16:17], v[12:13]
	v_pk_mul_f32 v[14:15], v[18:19], v[14:15]
	global_store_dwordx4 v[20:21], v[12:15], off
	s_nop 1
	v_mov_b64_e32 v[12:13], v[216:217]
	v_mov_b64_e32 v[14:15], v[218:219]
	v_pk_mul_f32 v[10:11], v[10:11], v[22:23] op_sel_hi:[1,0]
	v_pk_mul_f32 v[8:9], v[8:9], v[22:23] op_sel_hi:[1,0]
	v_pk_mul_f32 v[6:7], v[6:7], v[22:23] op_sel_hi:[1,0]
	v_pk_mul_f32 v[4:5], v[4:5], v[22:23] op_sel_hi:[1,0]
	v_pk_mul_f32 v[2:3], v[2:3], v[22:23] op_sel_hi:[1,0]
	v_pk_mul_f32 v[0:1], v[0:1], v[22:23] op_sel_hi:[1,0]
	s_andn2_b64 vcc, exec, s[4:5]
	s_mov_b64 s[4:5], -1
	v_pk_mul_f32 v[8:9], v[12:13], v[8:9]
	v_pk_mul_f32 v[10:11], v[14:15], v[10:11]
	global_store_dwordx4 v[20:21], v[8:11], off offset:64
	s_nop 1
	v_mov_b64_e32 v[8:9], v[220:221]
	v_mov_b64_e32 v[10:11], v[222:223]
	v_pk_mul_f32 v[4:5], v[8:9], v[4:5]
	v_pk_mul_f32 v[6:7], v[10:11], v[6:7]
	global_store_dwordx4 v[20:21], v[4:7], off offset:512
	s_nop 1
	v_mov_b64_e32 v[4:5], v[224:225]
	v_mov_b64_e32 v[6:7], v[226:227]
	v_pk_mul_f32 v[0:1], v[4:5], v[0:1]
	v_pk_mul_f32 v[2:3], v[6:7], v[2:3]
	global_store_dwordx4 v[20:21], v[0:3], off offset:576
	s_cbranch_vccnz .LBB0_965
	s_and_b64 vcc, exec, s[0:1]
	s_cbranch_vccnz .LBB0_964
	s_barrier
	s_branch .LBB0_964
